# GEMM0 live K-loop rewritten: MFMAs interleaved with next-group ds_reads, tile k+2 global loads and tile k+1 ds_writes; LDS double buffer, one barrier per iteration
# speedup vs baseline: 1.0536x; 1.0298x over previous
.LBB0_372:
	s_mul_hi_i32 s0, s43, 0x55555556
	s_lshr_b32 s1, s0, 31
	s_add_i32 s0, s0, s1
	s_lshl_b32 s12, s0, 7
	s_mul_i32 s0, s0, 3
	s_sub_i32 s0, s43, s0
	v_mov_b32_e32 v1, v0
	s_lshl_b32 s44, s0, 3
	s_add_i32 s44, s44, s41
	s_waitcnt vmcnt(4)
	v_ashrrev_i32_e32 v8, 3, v1
	v_and_b32_e32 v9, 7, v1
	v_add_u32_e32 v4, s12, v8
	v_mov_b64_e32 v[2:3], s[66:67]
	s_lshl_b32 s13, s44, 7
	v_mad_i64_i32 v[2:3], s[0:1], v4, s58, v[2:3]
	v_lshlrev_b32_e32 v106, 4, v9
	v_lshl_add_u64 v[98:99], v[2:3], 0, v[106:107]
	v_add_u32_e32 v4, s13, v8
	v_mov_b64_e32 v[2:3], s[2:3]
	v_mad_i64_i32 v[2:3], s[0:1], v4, s58, v[2:3]
	s_mov_b32 s0, 0x11000
	s_nop 0
	v_add_co_u32_e32 v4, vcc, s0, v98
	s_mov_b32 s1, 0x22000
	s_nop 0
	v_addc_co_u32_e32 v5, vcc, 0, v99, vcc
	v_add_co_u32_e32 v6, vcc, s1, v98
	s_mov_b32 s4, 0x33000
	s_nop 0
	v_addc_co_u32_e32 v7, vcc, 0, v99, vcc
	global_load_dwordx4 v[62:65], v[98:99], off
	global_load_dwordx4 v[70:73], v[4:5], off
	global_load_dwordx4 v[74:77], v[6:7], off
	v_add_co_u32_e32 v4, vcc, s4, v98
	v_lshl_add_u64 v[100:101], v[2:3], 0, v[106:107]
	s_nop 0
	v_addc_co_u32_e32 v5, vcc, 0, v99, vcc
	v_add_co_u32_e32 v2, vcc, s0, v100
	global_load_dwordx4 v[78:81], v[4:5], off
	s_nop 0
	v_addc_co_u32_e32 v3, vcc, 0, v101, vcc
	v_add_co_u32_e32 v4, vcc, s1, v100
	global_load_dwordx4 v[82:85], v[100:101], off
	s_nop 0
	v_addc_co_u32_e32 v5, vcc, 0, v101, vcc
	global_load_dwordx4 v[86:89], v[2:3], off
	global_load_dwordx4 v[90:93], v[4:5], off
	v_add_co_u32_e32 v2, vcc, s4, v100
	v_lshrrev_b32_e32 v4, 5, v1
	s_nop 0
	v_addc_co_u32_e32 v3, vcc, 0, v101, vcc
	global_load_dwordx4 v[94:97], v[2:3], off
	v_ashrrev_i32_e32 v3, 4, v1
	s_waitcnt vmcnt(11)
	v_xor_b32_e32 v10, v3, v1
	v_and_b32_e32 v3, 1, v3
	v_and_b32_e32 v4, 6, v4
	v_lshrrev_b32_e32 v2, 4, v1
	v_bfe_u32 v102, v1, 4, 2
	v_bfe_u32 v5, v1, 1, 3
	v_bitop3_b32 v3, v3, v9, v4 bitop3:0x36
	v_ashrrev_i32_e32 v103, 7, v1
	v_lshlrev_b32_e32 v105, 7, v8
	v_bitop3_b32 v2, v2, v5, 3 bitop3:0x6c
	v_bitop3_b32 v5, v102, v5, 4 bitop3:0x36
	v_lshlrev_b32_e32 v4, 4, v10
	s_movk_i32 s0, 0x70
	v_lshlrev_b32_e32 v111, 4, v3
	v_and_b32_e32 v104, 15, v1
	v_lshlrev_b32_e32 v6, 1, v1
	v_and_b32_e32 v7, 0x43, v1
	v_lshlrev_b32_e32 v8, 13, v103
	v_lshlrev_b32_e32 v106, 4, v2
	v_lshlrev_b32_e32 v109, 4, v5
	v_and_or_b32 v110, v4, s0, v105
	v_or_b32_e32 v2, v105, v111
	v_lshlrev_b32_e32 v11, 7, v104
	v_and_or_b32 v6, v6, 24, v7
	v_or_b32_e32 v3, v106, v8
	v_or_b32_e32 v4, v109, v8
	v_lshlrev_b32_e32 v108, 7, v6
	s_mov_b64 s[0:1], 0
	v_add_u32_e32 v112, v3, v11
	v_add_u32_e32 v113, v4, v11
	s_waitcnt vmcnt(7)
	ds_write_b128 v110, v[62:65]
	s_waitcnt vmcnt(6)
	ds_write_b128 v110, v[70:73] offset:4096
	s_waitcnt vmcnt(5)
	ds_write_b128 v110, v[74:77] offset:8192
	s_waitcnt vmcnt(4)
	ds_write_b128 v110, v[78:81] offset:12288
	s_waitcnt vmcnt(3)
	ds_write_b128 v2, v[82:85] offset:16384
	s_waitcnt vmcnt(2)
	ds_write_b128 v2, v[86:89] offset:20480
	s_waitcnt vmcnt(1)
	ds_write_b128 v2, v[90:93] offset:24576
	s_waitcnt vmcnt(0)
	ds_write_b128 v2, v[94:97] offset:28672
	v_mov_b32_e32 v2, 0
	v_mov_b32_e32 v3, v2
	v_mov_b32_e32 v4, v2
	v_mov_b32_e32 v5, v2
	v_mov_b32_e32 v6, v2
	v_mov_b32_e32 v7, v2
	v_mov_b32_e32 v8, v2
	v_mov_b32_e32 v9, v2
	v_mov_b32_e32 v10, v2
	v_mov_b32_e32 v11, v2
	v_mov_b32_e32 v12, v2
	v_mov_b32_e32 v13, v2
	v_mov_b32_e32 v14, v2
	v_mov_b32_e32 v15, v2
	v_mov_b32_e32 v16, v2
	v_mov_b32_e32 v17, v2
	v_mov_b32_e32 v18, v2
	v_mov_b32_e32 v19, v2
	v_mov_b32_e32 v20, v2
	v_mov_b32_e32 v21, v2
	v_mov_b32_e32 v22, v2
	v_mov_b32_e32 v23, v2
	v_mov_b32_e32 v24, v2
	v_mov_b32_e32 v25, v2
	v_mov_b32_e32 v26, v2
	v_mov_b32_e32 v27, v2
	v_mov_b32_e32 v28, v2
	v_mov_b32_e32 v29, v2
	v_mov_b32_e32 v30, v2
	v_mov_b32_e32 v31, v2
	v_mov_b32_e32 v32, v2
	v_mov_b32_e32 v33, v2
	v_mov_b32_e32 v34, v2
	v_mov_b32_e32 v35, v2
	v_mov_b32_e32 v36, v2
	v_mov_b32_e32 v37, v2
	v_mov_b32_e32 v38, v2
	v_mov_b32_e32 v39, v2
	v_mov_b32_e32 v40, v2
	v_mov_b32_e32 v41, v2
	v_mov_b32_e32 v42, v2
	v_mov_b32_e32 v43, v2
	v_mov_b32_e32 v44, v2
	v_mov_b32_e32 v45, v2
	v_mov_b32_e32 v46, v2
	v_mov_b32_e32 v47, v2
	v_mov_b32_e32 v48, v2
	v_mov_b32_e32 v49, v2
	v_mov_b32_e32 v50, v2
	v_mov_b32_e32 v51, v2
	v_mov_b32_e32 v52, v2
	v_mov_b32_e32 v53, v2
	v_mov_b32_e32 v54, v2
	v_mov_b32_e32 v55, v2
	v_mov_b32_e32 v56, v2
	v_mov_b32_e32 v57, v2
	v_mov_b32_e32 v58, v2
	v_mov_b32_e32 v59, v2
	v_mov_b32_e32 v60, v2
	v_mov_b32_e32 v61, v2
	v_mov_b32_e32 v66, v2
	v_mov_b32_e32 v67, v2
	v_mov_b32_e32 v68, v2
	v_mov_b32_e32 v69, v2
	v_lshl_add_u64 v[224:225], v[98:99], 0, s[0:1]
	global_load_dwordx4 v[224:227], v[224:225], off offset:128
	s_add_u32 s6, s0, 0x11000
	s_addc_u32 s7, s1, 0
	v_lshl_add_u64 v[228:229], v[98:99], 0, s[6:7]
	global_load_dwordx4 v[228:231], v[228:229], off offset:128
	s_add_u32 vcc_lo, s0, 0x22000
	s_addc_u32 vcc_hi, s1, 0
	v_lshl_add_u64 v[232:233], v[98:99], 0, vcc
	global_load_dwordx4 v[232:235], v[232:233], off offset:128
	s_add_u32 s6, s0, 0x33000
	s_addc_u32 s7, s1, 0
	v_lshl_add_u64 v[236:237], v[98:99], 0, s[6:7]
	global_load_dwordx4 v[236:239], v[236:237], off offset:128
	v_lshl_add_u64 v[240:241], v[100:101], 0, s[0:1]
	global_load_dwordx4 v[240:243], v[240:241], off offset:128
	s_add_u32 vcc_lo, s0, 0x11000
	s_addc_u32 vcc_hi, s1, 0
	v_lshl_add_u64 v[244:245], v[100:101], 0, vcc
	global_load_dwordx4 v[244:247], v[244:245], off offset:128
	s_add_u32 s6, s0, 0x22000
	s_addc_u32 s7, s1, 0
	v_lshl_add_u64 v[248:249], v[100:101], 0, s[6:7]
	global_load_dwordx4 v[248:251], v[248:249], off offset:128
	s_add_u32 vcc_lo, s0, 0x33000
	s_addc_u32 vcc_hi, s1, 0
	v_lshl_add_u64 v[252:253], v[100:101], 0, vcc
	global_load_dwordx4 v[252:255], v[252:253], off offset:128
	v_add_u32_e32 v188, v106, v108
	v_add_u32_e32 v189, v109, v108
	v_add_u32_e32 v190, v105, v111
	s_waitcnt lgkmcnt(0)
	s_barrier
	s_branch .LBB0_374
.LBB0_374:
.Lgq_c:
	ds_read_b128 v[114:117], v188 offset:16384
	ds_read_b128 v[118:121], v188 offset:16896
	ds_read_b128 v[156:159], v188 offset:20480
	ds_read_b128 v[160:163], v188 offset:20992
	ds_read_b128 v[122:125], v112
	ds_read_b128 v[126:129], v112 offset:2048
	v_lshl_add_u64 v[62:63], v[98:99], 0, s[0:1]
	global_load_dwordx4 v[62:65], v[62:63], off offset:256
	s_add_u32 vcc_lo, s0, 0x11000
	s_addc_u32 vcc_hi, s1, 0
	v_lshl_add_u64 v[70:71], v[98:99], 0, vcc
	global_load_dwordx4 v[70:73], v[70:71], off offset:256
	s_waitcnt lgkmcnt(1)
	v_mfma_f32_16x16x32_bf16 v[66:69], v[114:117], v[122:125], v[66:69]
	v_mfma_f32_16x16x32_bf16 v[58:61], v[118:121], v[122:125], v[58:61]
	s_add_u32 s6, s0, 0x22000
	s_addc_u32 s7, s1, 0
	v_lshl_add_u64 v[74:75], v[98:99], 0, s[6:7]
	global_load_dwordx4 v[74:77], v[74:75], off offset:256
	v_mfma_f32_16x16x32_bf16 v[54:57], v[156:159], v[122:125], v[54:57]
	v_mfma_f32_16x16x32_bf16 v[50:53], v[160:163], v[122:125], v[50:53]
	s_waitcnt lgkmcnt(0)
	v_mfma_f32_16x16x32_bf16 v[46:49], v[114:117], v[126:129], v[46:49]
	ds_read_b128 v[180:183], v112 offset:4096
	ds_read_b128 v[184:187], v112 offset:6144
	v_mfma_f32_16x16x32_bf16 v[42:45], v[118:121], v[126:129], v[42:45]
	v_mfma_f32_16x16x32_bf16 v[38:41], v[156:159], v[126:129], v[38:41]
	s_add_u32 vcc_lo, s0, 0x33000
	s_addc_u32 vcc_hi, s1, 0
	v_lshl_add_u64 v[78:79], v[98:99], 0, vcc
	global_load_dwordx4 v[78:81], v[78:79], off offset:256
	v_mfma_f32_16x16x32_bf16 v[34:37], v[160:163], v[126:129], v[34:37]
	s_waitcnt lgkmcnt(1)
	v_mfma_f32_16x16x32_bf16 v[30:33], v[114:117], v[180:183], v[30:33]
	ds_read_b128 v[164:167], v189 offset:16384
	ds_read_b128 v[168:171], v189 offset:16896
	v_mfma_f32_16x16x32_bf16 v[26:29], v[118:121], v[180:183], v[26:29]
	v_lshl_add_u64 v[82:83], v[100:101], 0, s[0:1]
	global_load_dwordx4 v[82:85], v[82:83], off offset:256
	v_mfma_f32_16x16x32_bf16 v[22:25], v[156:159], v[180:183], v[22:25]
	ds_read_b128 v[172:175], v189 offset:20480
	ds_read_b128 v[176:179], v189 offset:20992
	v_mfma_f32_16x16x32_bf16 v[18:21], v[160:163], v[180:183], v[18:21]
	s_waitcnt lgkmcnt(4)
	v_mfma_f32_16x16x32_bf16 v[14:17], v[114:117], v[184:187], v[14:17]
	ds_read_b128 v[122:125], v113
	ds_read_b128 v[126:129], v113 offset:2048
	v_mfma_f32_16x16x32_bf16 v[10:13], v[118:121], v[184:187], v[10:13]
	v_mfma_f32_16x16x32_bf16 v[6:9], v[156:159], v[184:187], v[6:9]
	s_add_u32 vcc_lo, s0, 0x11000
	s_addc_u32 vcc_hi, s1, 0
	v_lshl_add_u64 v[86:87], v[100:101], 0, vcc
	global_load_dwordx4 v[86:89], v[86:87], off offset:256
	v_mfma_f32_16x16x32_bf16 v[2:5], v[160:163], v[184:187], v[2:5]
	s_waitcnt lgkmcnt(1)
	v_mfma_f32_16x16x32_bf16 v[66:69], v[164:167], v[122:125], v[66:69]
	v_mfma_f32_16x16x32_bf16 v[58:61], v[168:171], v[122:125], v[58:61]
	s_add_u32 s6, s0, 0x22000
	s_addc_u32 s7, s1, 0
	v_lshl_add_u64 v[90:91], v[100:101], 0, s[6:7]
	global_load_dwordx4 v[90:93], v[90:91], off offset:256
	v_mfma_f32_16x16x32_bf16 v[54:57], v[172:175], v[122:125], v[54:57]
	v_mfma_f32_16x16x32_bf16 v[50:53], v[176:179], v[122:125], v[50:53]
	s_waitcnt lgkmcnt(0)
	v_mfma_f32_16x16x32_bf16 v[46:49], v[164:167], v[126:129], v[46:49]
	ds_read_b128 v[180:183], v113 offset:4096
	ds_read_b128 v[184:187], v113 offset:6144
	v_mfma_f32_16x16x32_bf16 v[42:45], v[168:171], v[126:129], v[42:45]
	v_mfma_f32_16x16x32_bf16 v[38:41], v[172:175], v[126:129], v[38:41]
	s_add_u32 vcc_lo, s0, 0x33000
	s_addc_u32 vcc_hi, s1, 0
	v_lshl_add_u64 v[94:95], v[100:101], 0, vcc
	global_load_dwordx4 v[94:97], v[94:95], off offset:256
	v_mfma_f32_16x16x32_bf16 v[34:37], v[176:179], v[126:129], v[34:37]
	s_waitcnt lgkmcnt(1)
	v_mfma_f32_16x16x32_bf16 v[30:33], v[164:167], v[180:183], v[30:33]
	s_waitcnt vmcnt(15)
	ds_write_b128 v110, v[224:227] offset:32768
	v_mfma_f32_16x16x32_bf16 v[26:29], v[168:171], v[180:183], v[26:29]
	s_waitcnt vmcnt(14)
	ds_write_b128 v110, v[228:231] offset:36864
	v_mfma_f32_16x16x32_bf16 v[22:25], v[172:175], v[180:183], v[22:25]
	s_waitcnt vmcnt(13)
	ds_write_b128 v110, v[232:235] offset:40960
	v_mfma_f32_16x16x32_bf16 v[18:21], v[176:179], v[180:183], v[18:21]
	s_waitcnt vmcnt(12)
	ds_write_b128 v110, v[236:239] offset:45056
	s_waitcnt lgkmcnt(4)
	v_mfma_f32_16x16x32_bf16 v[14:17], v[164:167], v[184:187], v[14:17]
	s_waitcnt vmcnt(11)
	ds_write_b128 v190, v[240:243] offset:49168
	v_mfma_f32_16x16x32_bf16 v[10:13], v[168:171], v[184:187], v[10:13]
	s_waitcnt vmcnt(10)
	ds_write_b128 v190, v[244:247] offset:53264
	v_mfma_f32_16x16x32_bf16 v[6:9], v[172:175], v[184:187], v[6:9]
	s_waitcnt vmcnt(9)
	ds_write_b128 v190, v[248:251] offset:57360
	v_mfma_f32_16x16x32_bf16 v[2:5], v[176:179], v[184:187], v[2:5]
	s_waitcnt vmcnt(8)
	ds_write_b128 v190, v[252:255] offset:61456
	s_waitcnt lgkmcnt(0)
	s_barrier
	s_add_u32 s0, s0, 0x80
	s_addc_u32 s1, s1, 0
	ds_read_b128 v[114:117], v188 offset:49168
	ds_read_b128 v[118:121], v188 offset:49680
	ds_read_b128 v[156:159], v188 offset:53264
	ds_read_b128 v[160:163], v188 offset:53776
	ds_read_b128 v[122:125], v112 offset:32768
	ds_read_b128 v[126:129], v112 offset:34816
	v_lshl_add_u64 v[224:225], v[98:99], 0, s[0:1]
	global_load_dwordx4 v[224:227], v[224:225], off offset:256
	s_add_u32 vcc_lo, s0, 0x11000
	s_addc_u32 vcc_hi, s1, 0
	v_lshl_add_u64 v[228:229], v[98:99], 0, vcc
	global_load_dwordx4 v[228:231], v[228:229], off offset:256
	s_waitcnt lgkmcnt(1)
	v_mfma_f32_16x16x32_bf16 v[66:69], v[114:117], v[122:125], v[66:69]
	v_mfma_f32_16x16x32_bf16 v[58:61], v[118:121], v[122:125], v[58:61]
	s_add_u32 s6, s0, 0x22000
	s_addc_u32 s7, s1, 0
	v_lshl_add_u64 v[232:233], v[98:99], 0, s[6:7]
	global_load_dwordx4 v[232:235], v[232:233], off offset:256
	v_mfma_f32_16x16x32_bf16 v[54:57], v[156:159], v[122:125], v[54:57]
	v_mfma_f32_16x16x32_bf16 v[50:53], v[160:163], v[122:125], v[50:53]
	s_waitcnt lgkmcnt(0)
	v_mfma_f32_16x16x32_bf16 v[46:49], v[114:117], v[126:129], v[46:49]
	ds_read_b128 v[180:183], v112 offset:36864
	ds_read_b128 v[184:187], v112 offset:38912
	v_mfma_f32_16x16x32_bf16 v[42:45], v[118:121], v[126:129], v[42:45]
	v_mfma_f32_16x16x32_bf16 v[38:41], v[156:159], v[126:129], v[38:41]
	s_add_u32 vcc_lo, s0, 0x33000
	s_addc_u32 vcc_hi, s1, 0
	v_lshl_add_u64 v[236:237], v[98:99], 0, vcc
	global_load_dwordx4 v[236:239], v[236:237], off offset:256
	v_mfma_f32_16x16x32_bf16 v[34:37], v[160:163], v[126:129], v[34:37]
	s_waitcnt lgkmcnt(1)
	v_mfma_f32_16x16x32_bf16 v[30:33], v[114:117], v[180:183], v[30:33]
	ds_read_b128 v[164:167], v189 offset:49168
	ds_read_b128 v[168:171], v189 offset:49680
	v_mfma_f32_16x16x32_bf16 v[26:29], v[118:121], v[180:183], v[26:29]
	v_lshl_add_u64 v[240:241], v[100:101], 0, s[0:1]
	global_load_dwordx4 v[240:243], v[240:241], off offset:256
	v_mfma_f32_16x16x32_bf16 v[22:25], v[156:159], v[180:183], v[22:25]
	ds_read_b128 v[172:175], v189 offset:53264
	ds_read_b128 v[176:179], v189 offset:53776
	v_mfma_f32_16x16x32_bf16 v[18:21], v[160:163], v[180:183], v[18:21]
	s_waitcnt lgkmcnt(4)
	v_mfma_f32_16x16x32_bf16 v[14:17], v[114:117], v[184:187], v[14:17]
	ds_read_b128 v[122:125], v113 offset:32768
	ds_read_b128 v[126:129], v113 offset:34816
	v_mfma_f32_16x16x32_bf16 v[10:13], v[118:121], v[184:187], v[10:13]
	v_mfma_f32_16x16x32_bf16 v[6:9], v[156:159], v[184:187], v[6:9]
	s_add_u32 vcc_lo, s0, 0x11000
	s_addc_u32 vcc_hi, s1, 0
	v_lshl_add_u64 v[244:245], v[100:101], 0, vcc
	global_load_dwordx4 v[244:247], v[244:245], off offset:256
	v_mfma_f32_16x16x32_bf16 v[2:5], v[160:163], v[184:187], v[2:5]
	s_waitcnt lgkmcnt(1)
	v_mfma_f32_16x16x32_bf16 v[66:69], v[164:167], v[122:125], v[66:69]
	v_mfma_f32_16x16x32_bf16 v[58:61], v[168:171], v[122:125], v[58:61]
	s_add_u32 s6, s0, 0x22000
	s_addc_u32 s7, s1, 0
	v_lshl_add_u64 v[248:249], v[100:101], 0, s[6:7]
	global_load_dwordx4 v[248:251], v[248:249], off offset:256
	v_mfma_f32_16x16x32_bf16 v[54:57], v[172:175], v[122:125], v[54:57]
	v_mfma_f32_16x16x32_bf16 v[50:53], v[176:179], v[122:125], v[50:53]
	s_waitcnt lgkmcnt(0)
	v_mfma_f32_16x16x32_bf16 v[46:49], v[164:167], v[126:129], v[46:49]
	ds_read_b128 v[180:183], v113 offset:36864
	ds_read_b128 v[184:187], v113 offset:38912
	v_mfma_f32_16x16x32_bf16 v[42:45], v[168:171], v[126:129], v[42:45]
	v_mfma_f32_16x16x32_bf16 v[38:41], v[172:175], v[126:129], v[38:41]
	s_add_u32 vcc_lo, s0, 0x33000
	s_addc_u32 vcc_hi, s1, 0
	v_lshl_add_u64 v[252:253], v[100:101], 0, vcc
	global_load_dwordx4 v[252:255], v[252:253], off offset:256
	v_mfma_f32_16x16x32_bf16 v[34:37], v[176:179], v[126:129], v[34:37]
	s_waitcnt lgkmcnt(1)
	v_mfma_f32_16x16x32_bf16 v[30:33], v[164:167], v[180:183], v[30:33]
	s_waitcnt vmcnt(15)
	ds_write_b128 v110, v[62:65]
	v_mfma_f32_16x16x32_bf16 v[26:29], v[168:171], v[180:183], v[26:29]
	s_waitcnt vmcnt(14)
	ds_write_b128 v110, v[70:73] offset:4096
	v_mfma_f32_16x16x32_bf16 v[22:25], v[172:175], v[180:183], v[22:25]
	s_waitcnt vmcnt(13)
	ds_write_b128 v110, v[74:77] offset:8192
	v_mfma_f32_16x16x32_bf16 v[18:21], v[176:179], v[180:183], v[18:21]
	s_waitcnt vmcnt(12)
	ds_write_b128 v110, v[78:81] offset:12288
	s_waitcnt lgkmcnt(4)
	v_mfma_f32_16x16x32_bf16 v[14:17], v[164:167], v[184:187], v[14:17]
	s_waitcnt vmcnt(11)
	ds_write_b128 v190, v[82:85] offset:16384
	v_mfma_f32_16x16x32_bf16 v[10:13], v[168:171], v[184:187], v[10:13]
	s_waitcnt vmcnt(10)
	ds_write_b128 v190, v[86:89] offset:20480
	v_mfma_f32_16x16x32_bf16 v[6:9], v[172:175], v[184:187], v[6:9]
	s_waitcnt vmcnt(9)
	ds_write_b128 v190, v[90:93] offset:24576
	v_mfma_f32_16x16x32_bf16 v[2:5], v[176:179], v[184:187], v[2:5]
	s_waitcnt vmcnt(8)
	ds_write_b128 v190, v[94:97] offset:28672
	s_waitcnt lgkmcnt(0)
	s_barrier
	s_add_u32 s0, s0, 0x80
	s_addc_u32 s1, s1, 0
	s_cmpk_lg_i32 s0, 0x700
	s_cbranch_scc1 .Lgq_c
	ds_read_b128 v[114:117], v188 offset:16384
	ds_read_b128 v[118:121], v188 offset:16896
	ds_read_b128 v[156:159], v188 offset:20480
	ds_read_b128 v[160:163], v188 offset:20992
	ds_read_b128 v[122:125], v112
	ds_read_b128 v[126:129], v112 offset:2048
	s_waitcnt lgkmcnt(1)
	v_mfma_f32_16x16x32_bf16 v[66:69], v[114:117], v[122:125], v[66:69]
	v_mfma_f32_16x16x32_bf16 v[58:61], v[118:121], v[122:125], v[58:61]
	v_mfma_f32_16x16x32_bf16 v[54:57], v[156:159], v[122:125], v[54:57]
	v_mfma_f32_16x16x32_bf16 v[50:53], v[160:163], v[122:125], v[50:53]
	s_waitcnt lgkmcnt(0)
	v_mfma_f32_16x16x32_bf16 v[46:49], v[114:117], v[126:129], v[46:49]
	ds_read_b128 v[180:183], v112 offset:4096
	ds_read_b128 v[184:187], v112 offset:6144
	v_mfma_f32_16x16x32_bf16 v[42:45], v[118:121], v[126:129], v[42:45]
	v_mfma_f32_16x16x32_bf16 v[38:41], v[156:159], v[126:129], v[38:41]
	v_mfma_f32_16x16x32_bf16 v[34:37], v[160:163], v[126:129], v[34:37]
	s_waitcnt lgkmcnt(1)
	v_mfma_f32_16x16x32_bf16 v[30:33], v[114:117], v[180:183], v[30:33]
	ds_read_b128 v[164:167], v189 offset:16384
	ds_read_b128 v[168:171], v189 offset:16896
	v_mfma_f32_16x16x32_bf16 v[26:29], v[118:121], v[180:183], v[26:29]
	v_mfma_f32_16x16x32_bf16 v[22:25], v[156:159], v[180:183], v[22:25]
	ds_read_b128 v[172:175], v189 offset:20480
	ds_read_b128 v[176:179], v189 offset:20992
	v_mfma_f32_16x16x32_bf16 v[18:21], v[160:163], v[180:183], v[18:21]
	s_waitcnt lgkmcnt(4)
	v_mfma_f32_16x16x32_bf16 v[14:17], v[114:117], v[184:187], v[14:17]
	ds_read_b128 v[122:125], v113
	ds_read_b128 v[126:129], v113 offset:2048
	v_mfma_f32_16x16x32_bf16 v[10:13], v[118:121], v[184:187], v[10:13]
	v_mfma_f32_16x16x32_bf16 v[6:9], v[156:159], v[184:187], v[6:9]
	v_mfma_f32_16x16x32_bf16 v[2:5], v[160:163], v[184:187], v[2:5]
	s_waitcnt lgkmcnt(1)
	v_mfma_f32_16x16x32_bf16 v[66:69], v[164:167], v[122:125], v[66:69]
	v_mfma_f32_16x16x32_bf16 v[58:61], v[168:171], v[122:125], v[58:61]
	v_mfma_f32_16x16x32_bf16 v[54:57], v[172:175], v[122:125], v[54:57]
	v_mfma_f32_16x16x32_bf16 v[50:53], v[176:179], v[122:125], v[50:53]
	s_waitcnt lgkmcnt(0)
	v_mfma_f32_16x16x32_bf16 v[46:49], v[164:167], v[126:129], v[46:49]
	ds_read_b128 v[180:183], v113 offset:4096
	ds_read_b128 v[184:187], v113 offset:6144
	v_mfma_f32_16x16x32_bf16 v[42:45], v[168:171], v[126:129], v[42:45]
	v_mfma_f32_16x16x32_bf16 v[38:41], v[172:175], v[126:129], v[38:41]
	v_mfma_f32_16x16x32_bf16 v[34:37], v[176:179], v[126:129], v[34:37]
	s_waitcnt lgkmcnt(1)
	v_mfma_f32_16x16x32_bf16 v[30:33], v[164:167], v[180:183], v[30:33]
	s_waitcnt vmcnt(7)
	ds_write_b128 v110, v[224:227] offset:32768
	v_mfma_f32_16x16x32_bf16 v[26:29], v[168:171], v[180:183], v[26:29]
	s_waitcnt vmcnt(6)
	ds_write_b128 v110, v[228:231] offset:36864
	v_mfma_f32_16x16x32_bf16 v[22:25], v[172:175], v[180:183], v[22:25]
	s_waitcnt vmcnt(5)
	ds_write_b128 v110, v[232:235] offset:40960
	v_mfma_f32_16x16x32_bf16 v[18:21], v[176:179], v[180:183], v[18:21]
	s_waitcnt vmcnt(4)
	ds_write_b128 v110, v[236:239] offset:45056
	s_waitcnt lgkmcnt(4)
	v_mfma_f32_16x16x32_bf16 v[14:17], v[164:167], v[184:187], v[14:17]
	s_waitcnt vmcnt(3)
	ds_write_b128 v190, v[240:243] offset:49168
	v_mfma_f32_16x16x32_bf16 v[10:13], v[168:171], v[184:187], v[10:13]
	s_waitcnt vmcnt(2)
	ds_write_b128 v190, v[244:247] offset:53264
	v_mfma_f32_16x16x32_bf16 v[6:9], v[172:175], v[184:187], v[6:9]
	s_waitcnt vmcnt(1)
	ds_write_b128 v190, v[248:251] offset:57360
	v_mfma_f32_16x16x32_bf16 v[2:5], v[176:179], v[184:187], v[2:5]
	s_waitcnt vmcnt(0)
	ds_write_b128 v190, v[252:255] offset:61456
	s_waitcnt lgkmcnt(0)
	s_barrier
	ds_read_b128 v[114:117], v188 offset:49168
	ds_read_b128 v[118:121], v188 offset:49680
	ds_read_b128 v[156:159], v188 offset:53264
	ds_read_b128 v[160:163], v188 offset:53776
	ds_read_b128 v[122:125], v112 offset:32768
	ds_read_b128 v[126:129], v112 offset:34816
	s_waitcnt lgkmcnt(1)
	v_mfma_f32_16x16x32_bf16 v[66:69], v[114:117], v[122:125], v[66:69]
	v_mfma_f32_16x16x32_bf16 v[58:61], v[118:121], v[122:125], v[58:61]
	v_mfma_f32_16x16x32_bf16 v[54:57], v[156:159], v[122:125], v[54:57]
	v_mfma_f32_16x16x32_bf16 v[50:53], v[160:163], v[122:125], v[50:53]
	s_waitcnt lgkmcnt(0)
	v_mfma_f32_16x16x32_bf16 v[46:49], v[114:117], v[126:129], v[46:49]
	ds_read_b128 v[180:183], v112 offset:36864
	ds_read_b128 v[184:187], v112 offset:38912
	v_mfma_f32_16x16x32_bf16 v[42:45], v[118:121], v[126:129], v[42:45]
	v_mfma_f32_16x16x32_bf16 v[38:41], v[156:159], v[126:129], v[38:41]
	v_mfma_f32_16x16x32_bf16 v[34:37], v[160:163], v[126:129], v[34:37]
	s_waitcnt lgkmcnt(1)
	v_mfma_f32_16x16x32_bf16 v[30:33], v[114:117], v[180:183], v[30:33]
	ds_read_b128 v[164:167], v189 offset:49168
	ds_read_b128 v[168:171], v189 offset:49680
	v_mfma_f32_16x16x32_bf16 v[26:29], v[118:121], v[180:183], v[26:29]
	v_mfma_f32_16x16x32_bf16 v[22:25], v[156:159], v[180:183], v[22:25]
	ds_read_b128 v[172:175], v189 offset:53264
	ds_read_b128 v[176:179], v189 offset:53776
	v_mfma_f32_16x16x32_bf16 v[18:21], v[160:163], v[180:183], v[18:21]
	s_waitcnt lgkmcnt(4)
	v_mfma_f32_16x16x32_bf16 v[14:17], v[114:117], v[184:187], v[14:17]
	ds_read_b128 v[122:125], v113 offset:32768
	ds_read_b128 v[126:129], v113 offset:34816
	v_mfma_f32_16x16x32_bf16 v[10:13], v[118:121], v[184:187], v[10:13]
	v_mfma_f32_16x16x32_bf16 v[6:9], v[156:159], v[184:187], v[6:9]
	v_mfma_f32_16x16x32_bf16 v[2:5], v[160:163], v[184:187], v[2:5]
	s_waitcnt lgkmcnt(1)
	v_mfma_f32_16x16x32_bf16 v[66:69], v[164:167], v[122:125], v[66:69]
	v_mfma_f32_16x16x32_bf16 v[58:61], v[168:171], v[122:125], v[58:61]
	v_mfma_f32_16x16x32_bf16 v[54:57], v[172:175], v[122:125], v[54:57]
	v_mfma_f32_16x16x32_bf16 v[50:53], v[176:179], v[122:125], v[50:53]
	s_waitcnt lgkmcnt(0)
	v_mfma_f32_16x16x32_bf16 v[46:49], v[164:167], v[126:129], v[46:49]
	ds_read_b128 v[180:183], v113 offset:36864
	ds_read_b128 v[184:187], v113 offset:38912
	v_mfma_f32_16x16x32_bf16 v[42:45], v[168:171], v[126:129], v[42:45]
	v_mfma_f32_16x16x32_bf16 v[38:41], v[172:175], v[126:129], v[38:41]
	v_mfma_f32_16x16x32_bf16 v[34:37], v[176:179], v[126:129], v[34:37]
	s_waitcnt lgkmcnt(1)
	v_mfma_f32_16x16x32_bf16 v[30:33], v[164:167], v[180:183], v[30:33]
	v_mfma_f32_16x16x32_bf16 v[26:29], v[168:171], v[180:183], v[26:29]
	v_mfma_f32_16x16x32_bf16 v[22:25], v[172:175], v[180:183], v[22:25]
	v_mfma_f32_16x16x32_bf16 v[18:21], v[176:179], v[180:183], v[18:21]
	s_waitcnt lgkmcnt(0)
	v_mfma_f32_16x16x32_bf16 v[14:17], v[164:167], v[184:187], v[14:17]
	v_mfma_f32_16x16x32_bf16 v[10:13], v[168:171], v[184:187], v[10:13]
	v_mfma_f32_16x16x32_bf16 v[6:9], v[172:175], v[184:187], v[6:9]
	v_mfma_f32_16x16x32_bf16 v[2:5], v[176:179], v[184:187], v[2:5]
	s_barrier

	.amdhsa_kernel _Z14fwd_megakernel6Params
		.amdhsa_group_segment_fixed_size 65552
		.amdhsa_private_segment_fixed_size 0
		.amdhsa_kernarg_size 840
		.amdhsa_user_sgpr_count 2
		.amdhsa_user_sgpr_dispatch_ptr 0
		.amdhsa_user_sgpr_queue_ptr 0
		.amdhsa_user_sgpr_kernarg_segment_ptr 1
		.amdhsa_user_sgpr_dispatch_id 0
		.amdhsa_user_sgpr_kernarg_preload_length 0
		.amdhsa_user_sgpr_kernarg_preload_offset 0
		.amdhsa_user_sgpr_private_segment_size 0
		.amdhsa_uses_dynamic_stack 0
		.amdhsa_enable_private_segment 0
		.amdhsa_system_sgpr_workgroup_id_x 1
		.amdhsa_system_sgpr_workgroup_id_y 0
		.amdhsa_system_sgpr_workgroup_id_z 0
		.amdhsa_system_sgpr_workgroup_info 0
		.amdhsa_system_vgpr_workitem_id 0
		.amdhsa_next_free_vgpr 256
		.amdhsa_next_free_sgpr 100
		.amdhsa_accum_offset 256
		.amdhsa_reserve_vcc 1
		.amdhsa_float_round_mode_32 0
		.amdhsa_float_round_mode_16_64 0
		.amdhsa_float_denorm_mode_32 3
		.amdhsa_float_denorm_mode_16_64 3
		.amdhsa_dx10_clamp 1
		.amdhsa_ieee_mode 1
		.amdhsa_fp16_overflow 0
		.amdhsa_tg_split 0
		.amdhsa_exception_fp_ieee_invalid_op 0
		.amdhsa_exception_fp_denorm_src 0
		.amdhsa_exception_fp_ieee_div_zero 0
		.amdhsa_exception_fp_ieee_overflow 0
		.amdhsa_exception_fp_ieee_underflow 0
		.amdhsa_exception_fp_ieee_inexact 0
		.amdhsa_exception_int_div_zero 0
	.end_amdhsa_kernel

amdhsa.kernels:
  - .agpr_count:     0
    .args:
      - .offset:         0
        .size:           584
        .value_kind:     by_value
      - .offset:         584
        .size:           4
        .value_kind:     hidden_block_count_x
      - .offset:         588
        .size:           4
        .value_kind:     hidden_block_count_y
      - .offset:         592
        .size:           4
        .value_kind:     hidden_block_count_z
      - .offset:         596
        .size:           2
        .value_kind:     hidden_group_size_x
      - .offset:         598
        .size:           2
        .value_kind:     hidden_group_size_y
      - .offset:         600
        .size:           2
        .value_kind:     hidden_group_size_z
      - .offset:         602
        .size:           2
        .value_kind:     hidden_remainder_x
      - .offset:         604
        .size:           2
        .value_kind:     hidden_remainder_y
      - .offset:         606
        .size:           2
        .value_kind:     hidden_remainder_z
      - .offset:         624
        .size:           8
        .value_kind:     hidden_global_offset_x
      - .offset:         632
        .size:           8
        .value_kind:     hidden_global_offset_y
      - .offset:         640
        .size:           8
        .value_kind:     hidden_global_offset_z
      - .offset:         648
        .size:           2
        .value_kind:     hidden_grid_dims
    .group_segment_fixed_size: 65552
    .kernarg_segment_align: 8
    .kernarg_segment_size: 840
    .language:       OpenCL C
    .language_version:
      - 2
      - 0
    .max_flat_workgroup_size: 256
    .name:           _Z14fwd_megakernel6Params
    .private_segment_fixed_size: 0
    .sgpr_count:     106
    .sgpr_spill_count: 452
    .symbol:         _Z14fwd_megakernel6Params.kd
    .uniform_work_group_size: 1
    .uses_dynamic_stack: false
    .vgpr_count:     256
    .vgpr_spill_count: 0
    .wavefront_size: 64
